# diff-attention tile loop top: vmcnt(0) and lgkmcnt(0) merged into one s_waitcnt before the per-tile barrier
# baseline (speedup 1.0000x reference)
; template <bool DIFF> ...
;     ...
;     for (int kt = DIFF ? nkt - 1 : 0; DIFF ? (kt >= 0) : (kt < nkt); kt += DIFF ? -1 : 1, ++it) {
;         if (DIFF) asm volatile("s_waitcnt vmcnt(0)" ::: "memory");
;         __syncthreads();
;         if (DIFF) { if (kt > 0) ATT_DMA(kt - 1, (it + 1) & 1); }
.LBB0_114:
	s_add_i32 s0, s20, s22
	s_cmp_eq_u32 s0, 0
	s_waitcnt vmcnt(0) lgkmcnt(0)
	s_barrier
	s_cbranch_scc1 .LBB0_116
	s_andn2_b32 s0, 0x8000, s28
	s_add_i32 s0, s0, 0
	s_add_i32 s1, s0, s21
	s_mov_b32 m0, s1
	s_add_i32 s0, s0, s14
	global_load_lds_dwordx4 v[236:237], off
	s_add_i32 m0, s1, 0x4000
	s_nop 0
	global_load_lds_dwordx4 v[238:239], off
	s_mov_b32 m0, s0
	s_nop 0
	global_load_lds_dwordx4 v[240:241], off
	s_add_i32 m0, s0, 0x4000
	s_nop 0
	global_load_lds_dwordx4 v[242:243], off
